# gate/up epilogue: per-row rstd computed without exec-masked blocks and without rsqrtf's denormal-range scaling (argument >= eps)
# speedup vs baseline: 1.0043x; 1.0043x over previous
; #define LAS __attribute__((address_space(3)))
;     DI void operator()(const AccT& acc, const Unit& u, int wr, int wc, int fr, int fq, LAS unsigned char* ldsx) const {
;     ...
;             for (int m = 0; m < 4; ++m) { const int tok = tok0 + 128 * ai + 16 * m; const bool ok = tok >= 0 && tok < (prompt ? SEQ : MTOK);
;                 rs[ai][m] = ok ? rsqrtf(sumsq[ok ? tok : 0] * (1.f / DM) + EPS) : 0.f; }
;         if (prompt) {
;             if (fr >= 14) {
; #pragma unroll
;                 for (int ai = 0; ai < 2; ++ai)
; #pragma unroll
;                     for (int n = 0; n < 2; ++n) *(LAS f32x4*)(H + ((ai * 2 + wr) * 4 + wc) * 64 + (fr - 14) * 32 + 16 * n + 4 * fq) = acc[ai][0][3][n] * rs[ai][3];
;             }
.LBB0_849:
	s_or_b64 exec, exec, s[28:29]
	s_waitcnt vmcnt(0)
	s_mov_b32 s30, 0x800000
	v_fmamk_f32 v160, v214, 0x3a800000, v236
	v_cmp_gt_u32_e32 vcc, s23, v172
	v_rsq_f32_e32 v160, v160
	s_nop 0
	v_cndmask_b32_e32 v214, 0, v160, vcc
	v_fmamk_f32 v161, v210, 0x3a800000, v236
	v_cmp_gt_u32_e32 vcc, s23, v212
	v_rsq_f32_e32 v161, v161
	s_nop 0
	v_cndmask_b32_e32 v210, 0, v161, vcc
	v_fmamk_f32 v160, v208, 0x3a800000, v236
	v_cmp_gt_u32_e32 vcc, s23, v206
	v_rsq_f32_e32 v160, v160
	s_nop 0
	v_cndmask_b32_e32 v208, 0, v160, vcc
	v_fmamk_f32 v161, v202, 0x3a800000, v236
	v_cmp_gt_u32_e32 vcc, s23, v204
	v_rsq_f32_e32 v161, v161
	s_nop 0
	v_cndmask_b32_e32 v202, 0, v161, vcc
	v_fmamk_f32 v160, v200, 0x3a800000, v236
	v_cmp_gt_u32_e32 vcc, s23, v198
	v_rsq_f32_e32 v160, v160
	s_nop 0
	v_cndmask_b32_e32 v200, 0, v160, vcc
	v_fmamk_f32 v161, v192, 0x3a800000, v236
	v_cmp_gt_u32_e32 vcc, s23, v194
	v_rsq_f32_e32 v161, v161
	s_nop 0
	v_cndmask_b32_e32 v192, 0, v161, vcc
	v_fmamk_f32 v160, v190, 0x3a800000, v236
	v_cmp_gt_u32_e32 vcc, s23, v188
	v_rsq_f32_e32 v160, v160
	s_nop 0
	v_cndmask_b32_e32 v190, 0, v160, vcc
	v_fmamk_f32 v161, v184, 0x3a800000, v236
	v_cmp_gt_u32_e32 vcc, s23, v186
	v_rsq_f32_e32 v161, v161
	s_nop 0
	v_cndmask_b32_e32 v184, 0, v161, vcc
	s_mov_b32 s23, 0x800000
	v_cndmask_b32_e64 v160, 0, 1, s[0:1]
	v_cmp_ne_u32_e64 s[44:45], 1, v160
	s_andn2_b64 vcc, exec, s[0:1]
	s_cbranch_vccnz .LBB0_853
	s_mov_b64 s[0:1], exec
	v_readlane_b32 s28, v252, 0
	v_readlane_b32 s29, v252, 1
	s_and_b64 s[28:29], s[0:1], s[28:29]
	s_mov_b64 exec, s[28:29]
	s_cbranch_execz .LBB0_852
	v_pk_mul_f32 v[162:163], v[118:119], v[202:203] op_sel_hi:[1,0]
	v_pk_mul_f32 v[160:161], v[116:117], v[202:203] op_sel_hi:[1,0]
	ds_write_b128 v246, v[160:163]
	v_pk_mul_f32 v[162:163], v[38:39], v[202:203] op_sel_hi:[1,0]
	v_pk_mul_f32 v[160:161], v[36:37], v[202:203] op_sel_hi:[1,0]
	ds_write_b128 v246, v[160:163] offset:64
	v_pk_mul_f32 v[162:163], v[86:87], v[184:185] op_sel_hi:[1,0]
	v_pk_mul_f32 v[160:161], v[84:85], v[184:185] op_sel_hi:[1,0]
	v_add_u32_e32 v164, v242, v228
	ds_write_b128 v164, v[160:163] offset:256
	v_pk_mul_f32 v[162:163], v[6:7], v[184:185] op_sel_hi:[1,0]
	v_pk_mul_f32 v[160:161], v[4:5], v[184:185] op_sel_hi:[1,0]
	ds_write_b128 v164, v[160:163] offset:320
